# p1 K-loop: 8 phases merged into 4 (32 MFMAs per barrier interval, B1 read with B0/At0, 3 stages in Q2, vmcnt(8) waits)
# speedup vs baseline: 1.0113x; 1.0113x over previous
; DI int opaque_tid() { int t = threadIdx.x; asm volatile("" : "+v"(t)); return t; }
; #define PG8_STAGE(bufoff, gbase, voff) do { _Pragma("unroll") for (int _i = 0; _i < 2; ++_i) \
;         __builtin_amdgcn_global_load_lds((const unsigned*)((const char*)(gbase) + (voff)[_i]), (LAS unsigned*)(lds + (bufoff) + ldsw + _i * 8192), 16, 0, 0); } while (0)
; #define PG8_WAIT_V(n) asm volatile("s_waitcnt vmcnt(" #n ")" ::: "memory")
; #define PG8_BAR __builtin_amdgcn_s_barrier()
; template <class Epi>
; DI void gemm_phase(LAS unsigned char* lds, const Gemm g, const StaticOrder& S, const Epi& E) {
;     const int tid = opaque_tid(), wid = __builtin_amdgcn_readfirstlane(tid >> 6), lane = tid & 63, wr = wid >> 2, wc = wid & 3, fr = lane & 15, fq = lane >> 4;
;     const int K = g.K, nt = K / BK;
;     unsigned voffA[2], voffB[2];
; #pragma unroll
;     for (int i = 0; i < 2; ++i) { int R, C; stage_rc(tid * 16 + i * 8192, R, C); const int Rb = Epi::PERM ? ((R & ~31) + perm32(R & 31)) : R;
;         voffA[i] = (unsigned)(R * g.lda + C) * 2u; voffB[i] = (unsigned)(Rb * g.ldb + C) * 2u; }
;     const size_t kstep = (size_t)(BK * 2);
;     const size_t hstepA = (size_t)HALF * g.lda * 2, hstepB = (size_t)HALF * g.ldb * 2;
;     const size_t tstepA = 2 * hstepA, tstepB = 2 * hstepB;
;     const unsigned ldsw = (unsigned)wid * 1024u;
;     const int aoff = lds_byte(wr * 64 + fr, fq * 8), boff = lds_byte(wc * 32 + fr, fq * 8);
;     ...
;     PG8_STAGE(PG8_SB(0, 0), cB, voffB); PG8_STAGE(PG8_SA(0, 0), cA, voffA); PG8_STAGE(PG8_SB(0, 1), cB + hstepB, voffB); PG8_STAGE(PG8_SA(0, 1), cA + hstepA, voffA);
;     if (wr == 1) PG8_BAR;
;     PG8_WAIT_V(4); PG8_BAR;
;     PG8_STAGE(PG8_SB(1, 0), cB + kstep, voffB); PG8_STAGE(PG8_SA(1, 0), cA + kstep, voffA); PG8_STAGE(PG8_SB(1, 1), cB + hstepB + kstep, voffB);
;     PG8_WAIT_V(6); PG8_BAR;
.LBB0_109:
	s_lshl_b32 s0, s4, 5
	s_mov_b64 s[4:5], 0x80
	s_and_b32 s17, s0, 0x60
	s_add_i32 m0, s9, 0x18000
	v_lshl_add_u64 v[6:7], v[6:7], 0, s[4:5]
	s_lshl_b32 s16, s3, 13
	s_lshl_b32 s46, s17, 7
	s_waitcnt vmcnt(2)
	s_barrier
	global_load_lds_dwordx4 v[6:7], off
	v_lshl_add_u64 v[4:5], v[4:5], 0, s[4:5]
	s_add_i32 m0, s9, 0x1a000
	s_add_i32 s71, s9, 0x8000
	s_add_i32 s72, s9, 0xa000
	global_load_lds_dwordx4 v[4:5], off
	v_lshl_add_u64 v[2:3], v[2:3], 0, s[4:5]
	s_mov_b32 m0, s71
	s_add_u32 s0, s54, 0x80080
	global_load_lds_dwordx4 v[2:3], off
	v_lshl_add_u64 v[0:1], v[0:1], 0, s[4:5]
	s_mov_b32 m0, s72
	s_addc_u32 s1, s55, 0
	global_load_lds_dwordx4 v[0:1], off
	s_add_i32 m0, s9, 0x1c000
	v_lshl_add_u64 v[0:1], s[0:1], 0, v[132:133]
	global_load_lds_dwordx4 v[0:1], off
	v_lshl_add_u64 v[0:1], s[0:1], 0, v[128:129]
	s_add_i32 m0, s9, 0x1e000
	s_add_i32 s75, 0, 0x10000
	global_load_lds_dwordx4 v[0:1], off
	v_lshrrev_b32_e32 v1, 1, v9
	v_and_b32_e32 v1, 24, v1
	v_and_b32_e32 v0, 15, v9
	v_lshlrev_b32_e32 v2, 1, v1
	v_lshl_or_b32 v144, s3, 6, v0
	v_lshl_or_b32 v0, v0, 6, v2
	v_lshlrev_b32_e32 v2, 2, v9
	v_and_b32_e32 v2, 32, v2
	v_bitop3_b32 v3, v0, s16, v2 bitop3:0xde
	v_bitop3_b32 v145, v0, s46, v2 bitop3:0xde
	v_lshlrev_b32_e32 v0, 15, v13
	v_and_b32_e32 v0, 0xffff0000, v0
	v_or_b32_e32 v146, s17, v1
	v_lshl_add_u32 v0, v12, 12, v0
	v_and_b32_e32 v1, 1, v13
	v_lshl_or_b32 v0, v1, 6, v0
	v_lshl_add_u32 v136, v14, 1, v0
	v_lshlrev_b32_e32 v0, 15, v8
	v_and_b32_e32 v0, 0xffff0000, v0
	s_waitcnt vmcnt(6)
	v_lshl_add_u32 v0, v10, 12, v0
	v_and_b32_e32 v1, 1, v8
	v_lshl_or_b32 v0, v1, 6, v0
	s_add_i32 s76, 0, 0x14000
	s_sext_i32_i16 s78, s2
	s_ashr_i32 s73, s10, 31
	s_mov_b32 s74, s10
	v_mov_b32_e32 v137, v133
	v_lshl_add_u32 v138, v11, 1, v0
	v_mov_b32_e32 v139, v133
	v_mov_b64_e32 v[140:141], 0x1d80
	v_mov_b64_e32 v[142:143], 0x1d7f
	v_add_u32_e32 v147, s75, v145
	v_add_u32_e32 v148, 0, v3
	v_add_u32_e32 v149, s76, v145
	s_movk_i32 s77, 0x7600
	s_barrier

; #define PG8_STAGE(bufoff, gbase, voff) do { _Pragma("unroll") for (int _i = 0; _i < 2; ++_i) \
;         __builtin_amdgcn_global_load_lds((const unsigned*)((const char*)(gbase) + (voff)[_i]), (LAS unsigned*)(lds + (bufoff) + ldsw + _i * 8192), 16, 0, 0); } while (0)
; #define PG8_LDA(dst, b, h) do { _Pragma("unroll") for (int m = 0; m < 4; ++m) _Pragma("unroll") for (int k = 0; k < 2; ++k) dst[m][k] = *(const LAS bf16x8*)(lds + PG8_SA(b, h) + aoff + m * 2048 + k * 1024); } while (0)
; #define PG8_LDB(dst, b, h) do { _Pragma("unroll") for (int n = 0; n < 2; ++n) _Pragma("unroll") for (int k = 0; k < 2; ++k) dst[n][k] = *(const LAS bf16x8*)(lds + PG8_SB(b, h) + boff + n * 2048 + k * 1024); } while (0)
; #define PG8_MMA(ai, bj, At, Bt) do { __builtin_amdgcn_s_setprio(1); _Pragma("unroll") for (int m = 0; m < 4; ++m) _Pragma("unroll") for (int n = 0; n < 2; ++n) _Pragma("unroll") for (int k = 0; k < 2; ++k) \
;         acc[ai][bj][m][n] = __builtin_amdgcn_mfma_f32_16x16x32_bf16(Bt[n][k], At[m][k], acc[ai][bj][m][n], 0, 0, 0); __builtin_amdgcn_s_setprio(0); } while (0)
; #define PG8_WAIT_V(n) asm volatile("s_waitcnt vmcnt(" #n ")" ::: "memory")
; template <class Epi>
; DI void gemm_phase(LAS unsigned char* lds, const Gemm g, const StaticOrder& S, const Epi& E) {
;     ...
;         for (int t = 0; t < nt; t += 2) {
;             const bool last = (t == nt - 2);
;             const char* a1 = cA + (size_t)(t + 1) * kstep;
;             const char* a2 = last ? nA : cA + (size_t)(t + 2) * kstep; const char* b2 = last ? nB : cB + (size_t)(t + 2) * kstep;
;             const char* a3 = a2 + kstep; const char* b3 = b2 + kstep;
;             if constexpr (Epi::HAS_MID) { if (t == Epi::MID_T) E.mid(acc, cur, wr, wc, fr, fq); }
;             PG8_LDB(B0, 0, 0); PG8_SCHED; PG8_LDA(At, 0, 0); PG8_STAGE(PG8_SA(1, 1), a1 + hstepA, voffA);
;             PG8_WAIT_L(8); PG8_BAR; PG8_WAIT_L(0); PG8_MMA(0, 0, At, B0); PG8_BAR; PG8_SCHED;
;             PG8_LDB(B1, 0, 1); PG8_STAGE(PG8_SB(0, 0), b2, voffB);
;             PG8_BAR; PG8_WAIT_L(0); PG8_MMA(0, 1, At, B1); PG8_BAR;
;             PG8_LDA(At, 0, 1); PG8_STAGE(PG8_SA(0, 0), a2, voffA);
;             PG8_BAR; PG8_WAIT_L(0); PG8_MMA(1, 0, At, B0); PG8_BAR; PG8_SCHED;
;             PG8_STAGE(PG8_SB(0, 1), b2 + hstepB, voffB);
;             PG8_WAIT_V(6); PG8_BAR; PG8_MMA(1, 1, At, B1); PG8_BAR;
.LBB0_113:
	ds_read_b128 v[150:153], v147
	ds_read_b128 v[154:157], v147 offset:1024
	ds_read_b128 v[158:161], v147 offset:2048
	ds_read_b128 v[162:165], v147 offset:3072
	s_add_u32 s0, s52, 0xfff80080
	s_addc_u32 s1, s53, -1
	s_cmp_eq_u32 s83, 28
	s_cselect_b32 s57, s47, s1
	s_cselect_b32 s56, s79, s0
	s_cselect_b32 s55, s17, s82
	s_cselect_b32 s54, s80, s81
	ds_read_b128 v[166:169], v148
	ds_read_b128 v[174:177], v148 offset:1024
	ds_read_b128 v[178:181], v148 offset:2048
	ds_read_b128 v[182:185], v148 offset:3072
	ds_read_b128 v[186:189], v148 offset:4096
	ds_read_b128 v[190:193], v148 offset:5120
	ds_read_b128 v[194:197], v148 offset:6144
	ds_read_b128 v[198:201], v148 offset:7168
	s_waitcnt lgkmcnt(11)
	ds_read_b128 v[202:205], v149
	ds_read_b128 v[206:209], v149 offset:1024
	ds_read_b128 v[210:213], v149 offset:2048
	ds_read_b128 v[216:219], v149 offset:3072
	v_lshl_add_u64 v[238:239], s[52:53], 0, v[136:137]
	s_add_i32 m0, s9, 0xc000
	s_nop 0
	global_load_lds_dwordx4 v[238:239], off
	v_lshl_add_u64 v[238:239], s[52:53], 0, v[138:139]
	s_add_i32 m0, s9, 0xe000
	s_nop 0
	global_load_lds_dwordx4 v[238:239], off
	s_waitcnt lgkmcnt(0)
	s_waitcnt vmcnt(8)
	s_barrier
	v_mfma_f32_16x16x32_bf16 v[124:127], v[150:153], v[166:169], v[124:127]
	v_mfma_f32_16x16x32_bf16 v[120:123], v[158:161], v[166:169], v[120:123]
	v_mfma_f32_16x16x32_bf16 v[116:119], v[150:153], v[178:181], v[116:119]
	v_mfma_f32_16x16x32_bf16 v[112:115], v[158:161], v[178:181], v[112:115]
	v_mfma_f32_16x16x32_bf16 v[100:103], v[150:153], v[186:189], v[100:103]
	v_mfma_f32_16x16x32_bf16 v[96:99], v[158:161], v[186:189], v[96:99]
	v_mfma_f32_16x16x32_bf16 v[84:87], v[150:153], v[194:197], v[84:87]
	v_mfma_f32_16x16x32_bf16 v[80:83], v[158:161], v[194:197], v[80:83]
	v_mfma_f32_16x16x32_bf16 v[124:127], v[154:157], v[174:177], v[124:127]
	v_mfma_f32_16x16x32_bf16 v[120:123], v[162:165], v[174:177], v[120:123]
	v_mfma_f32_16x16x32_bf16 v[116:119], v[154:157], v[182:185], v[116:119]
	v_mfma_f32_16x16x32_bf16 v[112:115], v[162:165], v[182:185], v[112:115]
	v_mfma_f32_16x16x32_bf16 v[100:103], v[154:157], v[190:193], v[100:103]
	v_mfma_f32_16x16x32_bf16 v[96:99], v[162:165], v[190:193], v[96:99]
	v_mfma_f32_16x16x32_bf16 v[84:87], v[154:157], v[198:201], v[84:87]
	v_mfma_f32_16x16x32_bf16 v[80:83], v[162:165], v[198:201], v[80:83]
	v_mfma_f32_16x16x32_bf16 v[108:111], v[202:205], v[166:169], v[108:111]
	v_mfma_f32_16x16x32_bf16 v[104:107], v[210:213], v[166:169], v[104:107]
	v_mfma_f32_16x16x32_bf16 v[92:95], v[202:205], v[178:181], v[92:95]
	v_mfma_f32_16x16x32_bf16 v[88:91], v[210:213], v[178:181], v[88:91]
	v_mfma_f32_16x16x32_bf16 v[76:79], v[202:205], v[186:189], v[76:79]
	v_mfma_f32_16x16x32_bf16 v[72:75], v[210:213], v[186:189], v[72:75]
	v_mfma_f32_16x16x32_bf16 v[68:71], v[202:205], v[194:197], v[68:71]
	v_mfma_f32_16x16x32_bf16 v[64:67], v[210:213], v[194:197], v[64:67]
	v_mfma_f32_16x16x32_bf16 v[108:111], v[206:209], v[174:177], v[108:111]
	v_mfma_f32_16x16x32_bf16 v[104:107], v[216:219], v[174:177], v[104:107]
	v_mfma_f32_16x16x32_bf16 v[92:95], v[206:209], v[182:185], v[92:95]
	v_mfma_f32_16x16x32_bf16 v[88:91], v[216:219], v[182:185], v[88:91]
	v_mfma_f32_16x16x32_bf16 v[76:79], v[206:209], v[190:193], v[76:79]
	v_mfma_f32_16x16x32_bf16 v[72:75], v[216:219], v[190:193], v[72:75]
	v_mfma_f32_16x16x32_bf16 v[68:71], v[206:209], v[198:201], v[68:71]
	v_mfma_f32_16x16x32_bf16 v[64:67], v[216:219], v[198:201], v[64:67]
	s_barrier
	ds_read_b128 v[166:169], v148 offset:16384
	ds_read_b128 v[174:177], v148 offset:17408
	ds_read_b128 v[178:181], v148 offset:18432
	ds_read_b128 v[182:185], v148 offset:19456
	ds_read_b128 v[186:189], v148 offset:20480
	ds_read_b128 v[190:193], v148 offset:21504
	ds_read_b128 v[194:197], v148 offset:22528
	ds_read_b128 v[198:201], v148 offset:23552
	s_add_i32 s0, s75, s58
	v_lshl_add_u64 v[170:171], s[54:55], 0, v[132:133]
	s_mov_b32 m0, s0
	s_nop 0
	global_load_lds_dwordx4 v[170:171], off
	v_lshl_add_u64 v[220:221], s[54:55], 0, v[128:129]
	s_add_i32 m0, s0, 0x2000
	s_nop 0
	global_load_lds_dwordx4 v[220:221], off
	v_lshl_add_u64 v[222:223], s[56:57], 0, v[134:135]
	s_mov_b32 m0, s9
	s_nop 0
	global_load_lds_dwordx4 v[222:223], off
	v_lshl_add_u64 v[224:225], s[56:57], 0, v[130:131]
	s_mov_b32 m0, s61
	s_nop 0
	global_load_lds_dwordx4 v[224:225], off
	s_add_u32 s0, s54, 0x80000
	s_addc_u32 s1, s55, 0
	s_add_i32 s84, s76, s58
	v_lshl_add_u64 v[238:239], s[0:1], 0, v[132:133]
	s_mov_b32 m0, s84
	s_nop 0
	global_load_lds_dwordx4 v[238:239], off
	v_lshl_add_u64 v[238:239], s[0:1], 0, v[128:129]
	s_add_i32 m0, s84, 0x2000
	s_nop 0
	global_load_lds_dwordx4 v[238:239], off
	s_waitcnt lgkmcnt(0)
	s_waitcnt vmcnt(8)
	s_barrier
; #define PG8_STAGE(bufoff, gbase, voff) do { _Pragma("unroll") for (int _i = 0; _i < 2; ++_i) \
;         __builtin_amdgcn_global_load_lds((const unsigned*)((const char*)(gbase) + (voff)[_i]), (LAS unsigned*)(lds + (bufoff) + ldsw + _i * 8192), 16, 0, 0); } while (0)
; #define PG8_LDA(dst, b, h) do { _Pragma("unroll") for (int m = 0; m < 4; ++m) _Pragma("unroll") for (int k = 0; k < 2; ++k) dst[m][k] = *(const LAS bf16x8*)(lds + PG8_SA(b, h) + aoff + m * 2048 + k * 1024); } while (0)
; #define PG8_LDB(dst, b, h) do { _Pragma("unroll") for (int n = 0; n < 2; ++n) _Pragma("unroll") for (int k = 0; k < 2; ++k) dst[n][k] = *(const LAS bf16x8*)(lds + PG8_SB(b, h) + boff + n * 2048 + k * 1024); } while (0)
; #define PG8_MMA(ai, bj, At, Bt) do { __builtin_amdgcn_s_setprio(1); _Pragma("unroll") for (int m = 0; m < 4; ++m) _Pragma("unroll") for (int n = 0; n < 2; ++n) _Pragma("unroll") for (int k = 0; k < 2; ++k) \
;         acc[ai][bj][m][n] = __builtin_amdgcn_mfma_f32_16x16x32_bf16(Bt[n][k], At[m][k], acc[ai][bj][m][n], 0, 0, 0); __builtin_amdgcn_s_setprio(0); } while (0)
; #define PG8_WAIT_V(n) asm volatile("s_waitcnt vmcnt(" #n ")" ::: "memory")
; #define PG8_WAIT_L(n) asm volatile("s_waitcnt lgkmcnt(" #n ")" ::: "memory")
; #define PG8_BAR __builtin_amdgcn_s_barrier()
; #define PG8_SCHED __builtin_amdgcn_sched_barrier(0)
; template <class Epi>
; DI void gemm_phase(LAS unsigned char* lds, const Gemm g, const StaticOrder& S, const Epi& E) {
;     ...
;             PG8_BAR; PG8_WAIT_L(0); PG8_MMA(1, 0, At, B0); PG8_BAR; PG8_SCHED;
;             PG8_STAGE(PG8_SB(0, 1), b2 + hstepB, voffB);
;             PG8_WAIT_V(6); PG8_BAR; PG8_MMA(1, 1, At, B1); PG8_BAR;
;             PG8_LDB(B0, 1, 0); PG8_SCHED; PG8_LDA(At, 1, 0); PG8_STAGE(PG8_SA(0, 1), a2 + hstepA, voffA);
;             PG8_WAIT_L(8); PG8_BAR; PG8_WAIT_L(0); PG8_MMA(0, 0, At, B0); PG8_BAR; PG8_SCHED;
;             PG8_LDB(B1, 1, 1); PG8_STAGE(PG8_SB(1, 0), b3, voffB);
;             PG8_BAR; PG8_WAIT_L(0); PG8_MMA(0, 1, At, B1); PG8_BAR;
;             PG8_LDA(At, 1, 1); PG8_STAGE(PG8_SA(1, 0), a3, voffA);
;             PG8_BAR; PG8_WAIT_L(0); PG8_MMA(1, 0, At, B0); PG8_BAR; PG8_SCHED;
	v_mfma_f32_16x16x32_bf16 v[60:63], v[150:153], v[166:169], v[60:63]
	v_mfma_f32_16x16x32_bf16 v[56:59], v[158:161], v[166:169], v[56:59]
	v_mfma_f32_16x16x32_bf16 v[52:55], v[150:153], v[178:181], v[52:55]
	v_mfma_f32_16x16x32_bf16 v[48:51], v[158:161], v[178:181], v[48:51]
	v_mfma_f32_16x16x32_bf16 v[36:39], v[150:153], v[186:189], v[36:39]
	v_mfma_f32_16x16x32_bf16 v[32:35], v[158:161], v[186:189], v[32:35]
	v_mfma_f32_16x16x32_bf16 v[20:23], v[150:153], v[194:197], v[20:23]
	v_mfma_f32_16x16x32_bf16 v[16:19], v[158:161], v[194:197], v[16:19]
	v_mfma_f32_16x16x32_bf16 v[60:63], v[154:157], v[174:177], v[60:63]
	v_mfma_f32_16x16x32_bf16 v[56:59], v[162:165], v[174:177], v[56:59]
	v_mfma_f32_16x16x32_bf16 v[52:55], v[154:157], v[182:185], v[52:55]
	v_mfma_f32_16x16x32_bf16 v[48:51], v[162:165], v[182:185], v[48:51]
	v_mfma_f32_16x16x32_bf16 v[36:39], v[154:157], v[190:193], v[36:39]
	v_mfma_f32_16x16x32_bf16 v[32:35], v[162:165], v[190:193], v[32:35]
	v_mfma_f32_16x16x32_bf16 v[20:23], v[154:157], v[198:201], v[20:23]
	v_mfma_f32_16x16x32_bf16 v[16:19], v[162:165], v[198:201], v[16:19]
	v_mfma_f32_16x16x32_bf16 v[44:47], v[202:205], v[166:169], v[44:47]
	v_mfma_f32_16x16x32_bf16 v[40:43], v[210:213], v[166:169], v[40:43]
	v_mfma_f32_16x16x32_bf16 v[28:31], v[202:205], v[178:181], v[28:31]
	v_mfma_f32_16x16x32_bf16 v[24:27], v[210:213], v[178:181], v[24:27]
	v_mfma_f32_16x16x32_bf16 v[12:15], v[202:205], v[186:189], v[12:15]
	v_mfma_f32_16x16x32_bf16 v[8:11], v[210:213], v[186:189], v[8:11]
	v_mfma_f32_16x16x32_bf16 v[4:7], v[202:205], v[194:197], v[4:7]
	v_mfma_f32_16x16x32_bf16 v[0:3], v[210:213], v[194:197], v[0:3]
	v_mfma_f32_16x16x32_bf16 v[44:47], v[206:209], v[174:177], v[44:47]
	v_mfma_f32_16x16x32_bf16 v[40:43], v[216:219], v[174:177], v[40:43]
	v_mfma_f32_16x16x32_bf16 v[28:31], v[206:209], v[182:185], v[28:31]
	v_mfma_f32_16x16x32_bf16 v[24:27], v[216:219], v[182:185], v[24:27]
	v_mfma_f32_16x16x32_bf16 v[12:15], v[206:209], v[190:193], v[12:15]
	v_mfma_f32_16x16x32_bf16 v[8:11], v[216:219], v[190:193], v[8:11]
	v_mfma_f32_16x16x32_bf16 v[4:7], v[206:209], v[198:201], v[4:7]
	v_mfma_f32_16x16x32_bf16 v[0:3], v[216:219], v[198:201], v[0:3]
	s_barrier
	v_add_u32_e32 v252, 0x18000, v145
	v_add_u32_e32 v172, 0x1c000, v145
	ds_read_b128 v[150:153], v252
	ds_read_b128 v[154:157], v252 offset:1024
	ds_read_b128 v[158:161], v252 offset:2048
	ds_read_b128 v[162:165], v252 offset:3072
	ds_read_b128 v[166:169], v148 offset:32768
	ds_read_b128 v[174:177], v148 offset:33792
	ds_read_b128 v[178:181], v148 offset:34816
	ds_read_b128 v[182:185], v148 offset:35840
	ds_read_b128 v[186:189], v148 offset:36864
	ds_read_b128 v[190:193], v148 offset:37888
	ds_read_b128 v[194:197], v148 offset:38912
	ds_read_b128 v[198:201], v148 offset:39936
	s_waitcnt lgkmcnt(11)
	ds_read_b128 v[202:205], v172
	ds_read_b128 v[206:209], v172 offset:1024
	ds_read_b128 v[210:213], v172 offset:2048
	ds_read_b128 v[216:219], v172 offset:3072
	s_add_u32 s0, s56, 0x80000
	s_addc_u32 s1, s57, 0
	v_lshl_add_u64 v[238:239], s[0:1], 0, v[134:135]
	s_mov_b32 m0, s68
	s_nop 0
	global_load_lds_dwordx4 v[238:239], off
	v_lshl_add_u64 v[238:239], s[0:1], 0, v[130:131]
	s_mov_b32 m0, s69
	s_nop 0
	global_load_lds_dwordx4 v[238:239], off
	s_waitcnt lgkmcnt(0)
	s_waitcnt vmcnt(8)
	s_barrier
	v_mfma_f32_16x16x32_bf16 v[124:127], v[150:153], v[166:169], v[124:127]
	v_mfma_f32_16x16x32_bf16 v[120:123], v[158:161], v[166:169], v[120:123]
	v_mfma_f32_16x16x32_bf16 v[116:119], v[150:153], v[178:181], v[116:119]
	v_mfma_f32_16x16x32_bf16 v[112:115], v[158:161], v[178:181], v[112:115]
	v_mfma_f32_16x16x32_bf16 v[100:103], v[150:153], v[186:189], v[100:103]
	v_mfma_f32_16x16x32_bf16 v[96:99], v[158:161], v[186:189], v[96:99]
	v_mfma_f32_16x16x32_bf16 v[84:87], v[150:153], v[194:197], v[84:87]
	v_mfma_f32_16x16x32_bf16 v[80:83], v[158:161], v[194:197], v[80:83]
	v_mfma_f32_16x16x32_bf16 v[124:127], v[154:157], v[174:177], v[124:127]
	v_mfma_f32_16x16x32_bf16 v[120:123], v[162:165], v[174:177], v[120:123]
	v_mfma_f32_16x16x32_bf16 v[116:119], v[154:157], v[182:185], v[116:119]
	v_mfma_f32_16x16x32_bf16 v[112:115], v[162:165], v[182:185], v[112:115]
	v_mfma_f32_16x16x32_bf16 v[100:103], v[154:157], v[190:193], v[100:103]
	v_mfma_f32_16x16x32_bf16 v[96:99], v[162:165], v[190:193], v[96:99]
	v_mfma_f32_16x16x32_bf16 v[84:87], v[154:157], v[198:201], v[84:87]
	v_mfma_f32_16x16x32_bf16 v[80:83], v[162:165], v[198:201], v[80:83]
	v_mfma_f32_16x16x32_bf16 v[108:111], v[202:205], v[166:169], v[108:111]
	v_mfma_f32_16x16x32_bf16 v[104:107], v[210:213], v[166:169], v[104:107]
	v_mfma_f32_16x16x32_bf16 v[92:95], v[202:205], v[178:181], v[92:95]
	v_mfma_f32_16x16x32_bf16 v[88:91], v[210:213], v[178:181], v[88:91]
	v_mfma_f32_16x16x32_bf16 v[76:79], v[202:205], v[186:189], v[76:79]
	v_mfma_f32_16x16x32_bf16 v[72:75], v[210:213], v[186:189], v[72:75]
	v_mfma_f32_16x16x32_bf16 v[68:71], v[202:205], v[194:197], v[68:71]
	v_mfma_f32_16x16x32_bf16 v[64:67], v[210:213], v[194:197], v[64:67]
	v_mfma_f32_16x16x32_bf16 v[108:111], v[206:209], v[174:177], v[108:111]
	v_mfma_f32_16x16x32_bf16 v[104:107], v[216:219], v[174:177], v[104:107]
	v_mfma_f32_16x16x32_bf16 v[92:95], v[206:209], v[182:185], v[92:95]
	v_mfma_f32_16x16x32_bf16 v[88:91], v[216:219], v[182:185], v[88:91]
	v_mfma_f32_16x16x32_bf16 v[76:79], v[206:209], v[190:193], v[76:79]
	v_mfma_f32_16x16x32_bf16 v[72:75], v[216:219], v[190:193], v[72:75]
	v_mfma_f32_16x16x32_bf16 v[68:71], v[206:209], v[198:201], v[68:71]
	v_mfma_f32_16x16x32_bf16 v[64:67], v[216:219], v[198:201], v[64:67]
	s_barrier
; #define PG8_STAGE(bufoff, gbase, voff) do { _Pragma("unroll") for (int _i = 0; _i < 2; ++_i) \
;         __builtin_amdgcn_global_load_lds((const unsigned*)((const char*)(gbase) + (voff)[_i]), (LAS unsigned*)(lds + (bufoff) + ldsw + _i * 8192), 16, 0, 0); } while (0)
; #define PG8_LDA(dst, b, h) do { _Pragma("unroll") for (int m = 0; m < 4; ++m) _Pragma("unroll") for (int k = 0; k < 2; ++k) dst[m][k] = *(const LAS bf16x8*)(lds + PG8_SA(b, h) + aoff + m * 2048 + k * 1024); } while (0)
; #define PG8_LDB(dst, b, h) do { _Pragma("unroll") for (int n = 0; n < 2; ++n) _Pragma("unroll") for (int k = 0; k < 2; ++k) dst[n][k] = *(const LAS bf16x8*)(lds + PG8_SB(b, h) + boff + n * 2048 + k * 1024); } while (0)
; #define PG8_MMA(ai, bj, At, Bt) do { __builtin_amdgcn_s_setprio(1); _Pragma("unroll") for (int m = 0; m < 4; ++m) _Pragma("unroll") for (int n = 0; n < 2; ++n) _Pragma("unroll") for (int k = 0; k < 2; ++k) \
;         acc[ai][bj][m][n] = __builtin_amdgcn_mfma_f32_16x16x32_bf16(Bt[n][k], At[m][k], acc[ai][bj][m][n], 0, 0, 0); __builtin_amdgcn_s_setprio(0); } while (0)
; #define PG8_WAIT_V(n) asm volatile("s_waitcnt vmcnt(" #n ")" ::: "memory")
; #define PG8_WAIT_L(n) asm volatile("s_waitcnt lgkmcnt(" #n ")" ::: "memory")
; #define PG8_BAR __builtin_amdgcn_s_barrier()
; #define PG8_SCHED __builtin_amdgcn_sched_barrier(0)
; template <class Epi>
; DI void gemm_phase(LAS unsigned char* lds, const Gemm g, const StaticOrder& S, const Epi& E) {
;     ...
;             PG8_LDB(B1, 1, 1); PG8_STAGE(PG8_SB(1, 0), b3, voffB);
;             PG8_BAR; PG8_WAIT_L(0); PG8_MMA(0, 1, At, B1); PG8_BAR;
;             PG8_LDA(At, 1, 1); PG8_STAGE(PG8_SA(1, 0), a3, voffA);
;             PG8_BAR; PG8_WAIT_L(0); PG8_MMA(1, 0, At, B0); PG8_BAR; PG8_SCHED;
;             PG8_STAGE(PG8_SB(1, 1), b3 + hstepB, voffB);
;             PG8_WAIT_V(6); PG8_BAR; PG8_MMA(1, 1, At, B1); PG8_BAR;
;         }
	ds_read_b128 v[166:169], v148 offset:49152
	ds_read_b128 v[174:177], v148 offset:50176
	ds_read_b128 v[178:181], v148 offset:51200
	ds_read_b128 v[182:185], v148 offset:52224
	ds_read_b128 v[186:189], v148 offset:53248
	ds_read_b128 v[190:193], v148 offset:54272
	ds_read_b128 v[194:197], v148 offset:55296
	ds_read_b128 v[198:201], v148 offset:56320
	s_add_i32 s0, s58, 0x18000
	v_lshl_add_u64 v[238:239], v[170:171], 0, s[4:5]
	s_mov_b32 m0, s0
	s_nop 0
	global_load_lds_dwordx4 v[238:239], off
	v_lshl_add_u64 v[238:239], v[220:221], 0, s[4:5]
	s_add_i32 m0, s0, 0x2000
	s_nop 0
	global_load_lds_dwordx4 v[238:239], off
	v_lshl_add_u64 v[238:239], v[222:223], 0, s[4:5]
	s_mov_b32 m0, s71
	s_nop 0
	global_load_lds_dwordx4 v[238:239], off
	v_lshl_add_u64 v[238:239], v[224:225], 0, s[4:5]
	s_mov_b32 m0, s72
	s_nop 0
	global_load_lds_dwordx4 v[238:239], off
	s_add_u32 s0, s54, 0x80080
	s_addc_u32 s1, s55, 0
	s_add_i32 s84, s58, 0x1c000
	v_lshl_add_u64 v[238:239], s[0:1], 0, v[132:133]
	s_mov_b32 m0, s84
	s_nop 0
	global_load_lds_dwordx4 v[238:239], off
	v_lshl_add_u64 v[238:239], s[0:1], 0, v[128:129]
	s_add_i32 m0, s84, 0x2000
	s_nop 0
	global_load_lds_dwordx4 v[238:239], off
	s_waitcnt lgkmcnt(0)
	s_waitcnt vmcnt(8)
	s_add_i32 s83, s83, 2
	s_add_u32 s52, s52, 0x100
	s_addc_u32 s53, s53, 0
	s_add_u32 s81, s81, 0x100
	s_addc_u32 s82, s82, 0
	s_cmp_gt_u32 s83, 29
	s_barrier
	v_mfma_f32_16x16x32_bf16 v[60:63], v[150:153], v[166:169], v[60:63]
	v_mfma_f32_16x16x32_bf16 v[56:59], v[158:161], v[166:169], v[56:59]
	v_mfma_f32_16x16x32_bf16 v[52:55], v[150:153], v[178:181], v[52:55]
	v_mfma_f32_16x16x32_bf16 v[48:51], v[158:161], v[178:181], v[48:51]
	v_mfma_f32_16x16x32_bf16 v[36:39], v[150:153], v[186:189], v[36:39]
	v_mfma_f32_16x16x32_bf16 v[32:35], v[158:161], v[186:189], v[32:35]
	v_mfma_f32_16x16x32_bf16 v[20:23], v[150:153], v[194:197], v[20:23]
	v_mfma_f32_16x16x32_bf16 v[16:19], v[158:161], v[194:197], v[16:19]
	v_mfma_f32_16x16x32_bf16 v[60:63], v[154:157], v[174:177], v[60:63]
	v_mfma_f32_16x16x32_bf16 v[56:59], v[162:165], v[174:177], v[56:59]
	v_mfma_f32_16x16x32_bf16 v[52:55], v[154:157], v[182:185], v[52:55]
	v_mfma_f32_16x16x32_bf16 v[48:51], v[162:165], v[182:185], v[48:51]
	v_mfma_f32_16x16x32_bf16 v[36:39], v[154:157], v[190:193], v[36:39]
	v_mfma_f32_16x16x32_bf16 v[32:35], v[162:165], v[190:193], v[32:35]
	v_mfma_f32_16x16x32_bf16 v[20:23], v[154:157], v[198:201], v[20:23]
	v_mfma_f32_16x16x32_bf16 v[16:19], v[162:165], v[198:201], v[16:19]
	v_mfma_f32_16x16x32_bf16 v[44:47], v[202:205], v[166:169], v[44:47]
	v_mfma_f32_16x16x32_bf16 v[40:43], v[210:213], v[166:169], v[40:43]
	v_mfma_f32_16x16x32_bf16 v[28:31], v[202:205], v[178:181], v[28:31]
	v_mfma_f32_16x16x32_bf16 v[24:27], v[210:213], v[178:181], v[24:27]
	v_mfma_f32_16x16x32_bf16 v[12:15], v[202:205], v[186:189], v[12:15]
	v_mfma_f32_16x16x32_bf16 v[8:11], v[210:213], v[186:189], v[8:11]
	v_mfma_f32_16x16x32_bf16 v[4:7], v[202:205], v[194:197], v[4:7]
	v_mfma_f32_16x16x32_bf16 v[0:3], v[210:213], v[194:197], v[0:3]
	v_mfma_f32_16x16x32_bf16 v[44:47], v[206:209], v[174:177], v[44:47]
	v_mfma_f32_16x16x32_bf16 v[40:43], v[216:219], v[174:177], v[40:43]
	v_mfma_f32_16x16x32_bf16 v[28:31], v[206:209], v[182:185], v[28:31]
	v_mfma_f32_16x16x32_bf16 v[24:27], v[216:219], v[182:185], v[24:27]
	v_mfma_f32_16x16x32_bf16 v[12:15], v[206:209], v[190:193], v[12:15]
	v_mfma_f32_16x16x32_bf16 v[8:11], v[216:219], v[190:193], v[8:11]
	v_mfma_f32_16x16x32_bf16 v[4:7], v[206:209], v[198:201], v[4:7]
	v_mfma_f32_16x16x32_bf16 v[0:3], v[216:219], v[198:201], v[0:3]
	s_barrier
	s_cbranch_scc0 .LBB0_113
; DI unsigned pk2(float lo, float hi) { f32x2 v = {lo, hi}; bf16x2_t b = __builtin_convertvector(v, bf16x2_t); return __builtin_bit_cast(unsigned, b); }
; #define PG8_WAIT_V(n) asm volatile("s_waitcnt vmcnt(" #n ")" ::: "memory")
; #define PG8_BAR __builtin_amdgcn_s_barrier()
; template <class Epi>
; DI void gemm_phase(LAS unsigned char* lds, const Gemm g, const StaticOrder& S, const Epi& E) {
;     ...
;         E(acc, cur, wr, wc, fr, fq);
;         if (!has_next) break;
; #pragma unroll
;         for (int a = 0; a < 2; ++a)
; #pragma unroll
;             for (int b = 0; b < 2; ++b)
; #pragma unroll
;                 for (int m = 0; m < 4; ++m)
; #pragma unroll
;                     for (int n = 0; n < 2; ++n) acc[a][b][m][n] = (f32x4){0.f, 0.f, 0.f, 0.f};
;         cur = nxt; cA = nA; cB = nB; ++ui;
;     }
;     PG8_WAIT_V(0);
;     if (wr == 0) PG8_BAR;
;     PG8_BAR;
;     DI void operator()(const f32x4 (&acc)[2][2][4][2], const Unit& u, int wr, int wc, int fr, int fq) const {
;         const int row0 = u.pm * BM + wr * 64 + fr, col0 = u.pn * BM + wc * 32 + 8 * fq;
; #pragma unroll
;         for (int ai = 0; ai < 2; ++ai)
; #pragma unroll
;             for (int m = 0; m < 4; ++m) { bf16_t* rowp = O + (size_t)(row0 + ai * HALF + m * 16) * ldc + col0;
; #pragma unroll
;                 for (int bj = 0; bj < 2; ++bj) { const f32x4 v0 = acc[ai][bj][m][0], v1 = acc[ai][bj][m][1];
;                     u32x4 w; w.x = pk2(v0[0], v0[1]); w.y = pk2(v0[2], v0[3]); w.z = pk2(v1[0], v1[1]); w.w = pk2(v1[2], v1[3]);
;                     *(u32x4*)(rowp + bj * HALF) = w; } }
	v_lshl_add_u32 v156, s8, 8, v144
	v_lshl_or_b32 v150, s78, 8, v146
	v_ashrrev_i32_e32 v151, 31, v150
	v_mov_b64_e32 v[152:153], s[30:31]
	v_cvt_pk_bf16_f32 v68, v68, v69
	v_cvt_pk_bf16_f32 v69, v70, v71
	v_cvt_pk_bf16_f32 v70, v64, v65
	v_add_u32_e32 v64, 0x80, v156
	v_mad_i64_i32 v[154:155], s[0:1], v156, s77, v[152:153]
	v_lshlrev_b64 v[150:151], 1, v[150:151]
	v_cvt_pk_bf16_f32 v108, v108, v109
	v_cvt_pk_bf16_f32 v109, v110, v111
	v_cvt_pk_bf16_f32 v110, v104, v105
	v_or_b32_e32 v104, 16, v156
	v_mad_i64_i32 v[64:65], s[0:1], v64, s77, v[152:153]
	v_cvt_pk_bf16_f32 v44, v44, v45
	v_cvt_pk_bf16_f32 v45, v46, v47
	v_cvt_pk_bf16_f32 v46, v40, v41
	v_add_u32_e32 v40, 0x90, v156
	v_lshl_add_u64 v[154:155], v[154:155], 0, v[150:151]
	v_cvt_pk_bf16_f32 v111, v106, v107
	v_mad_i64_i32 v[104:105], s[0:1], v104, s77, v[152:153]
	v_cvt_pk_bf16_f32 v92, v92, v93
	v_cvt_pk_bf16_f32 v93, v94, v95
	v_cvt_pk_bf16_f32 v94, v88, v89
	v_or_b32_e32 v88, 32, v156
	v_lshl_add_u64 v[64:65], v[64:65], 0, v[150:151]
	v_cvt_pk_bf16_f32 v47, v42, v43
	v_mad_i64_i32 v[40:41], s[0:1], v40, s77, v[152:153]
	v_cvt_pk_bf16_f32 v28, v28, v29
	v_cvt_pk_bf16_f32 v29, v30, v31
	v_cvt_pk_bf16_f32 v30, v24, v25
	v_add_u32_e32 v24, 0xa0, v156
	global_store_dwordx4 v[154:155], v[108:111], off offset:256 nt
	v_cvt_pk_bf16_f32 v95, v90, v91
	v_mad_i64_i32 v[88:89], s[0:1], v88, s77, v[152:153]
	v_lshl_add_u64 v[108:109], v[104:105], 0, v[150:151]
	v_cvt_pk_bf16_f32 v76, v76, v77
	v_cvt_pk_bf16_f32 v77, v78, v79
	v_cvt_pk_bf16_f32 v78, v72, v73
	v_or_b32_e32 v72, 48, v156
	global_store_dwordx4 v[64:65], v[44:47], off offset:256 nt
	v_cvt_pk_bf16_f32 v31, v26, v27
	v_mad_i64_i32 v[24:25], s[0:1], v24, s77, v[152:153]
	v_lshl_add_u64 v[44:45], v[40:41], 0, v[150:151]
	v_cvt_pk_bf16_f32 v12, v12, v13
	v_cvt_pk_bf16_f32 v13, v14, v15
	v_cvt_pk_bf16_f32 v14, v8, v9
	v_add_u32_e32 v8, 0xb0, v156
	global_store_dwordx4 v[108:109], v[92:95], off offset:256 nt
	v_cvt_pk_bf16_f32 v79, v74, v75
	v_mad_i64_i32 v[72:73], s[0:1], v72, s77, v[152:153]
	v_lshl_add_u64 v[92:93], v[88:89], 0, v[150:151]
	global_store_dwordx4 v[44:45], v[28:31], off offset:256 nt
	v_cvt_pk_bf16_f32 v15, v10, v11
	v_mad_i64_i32 v[8:9], s[0:1], v8, s77, v[152:153]
	v_lshl_add_u64 v[28:29], v[24:25], 0, v[150:151]
	v_cvt_pk_bf16_f32 v124, v124, v125
	v_cvt_pk_bf16_f32 v125, v126, v127
	v_cvt_pk_bf16_f32 v126, v120, v121
	v_cvt_pk_bf16_f32 v127, v122, v123
	v_cvt_pk_bf16_f32 v104, v116, v117
	v_cvt_pk_bf16_f32 v105, v118, v119
	v_cvt_pk_bf16_f32 v106, v112, v113
	v_cvt_pk_bf16_f32 v107, v114, v115
	v_cvt_pk_bf16_f32 v88, v100, v101
	v_cvt_pk_bf16_f32 v89, v102, v103
	v_cvt_pk_bf16_f32 v90, v96, v97
	v_cvt_pk_bf16_f32 v91, v98, v99
	global_store_dwordx4 v[92:93], v[76:79], off offset:256 nt
	v_cvt_pk_bf16_f32 v74, v80, v81
	v_cvt_pk_bf16_f32 v75, v82, v83
	v_lshl_add_u64 v[76:77], v[72:73], 0, v[150:151]
	v_cvt_pk_bf16_f32 v72, v84, v85
	v_cvt_pk_bf16_f32 v73, v86, v87
	v_cvt_pk_bf16_f32 v71, v66, v67
	v_cvt_pk_bf16_f32 v60, v60, v61
	v_cvt_pk_bf16_f32 v61, v62, v63
	v_cvt_pk_bf16_f32 v62, v56, v57
	v_cvt_pk_bf16_f32 v63, v58, v59
	v_cvt_pk_bf16_f32 v40, v52, v53
	v_cvt_pk_bf16_f32 v41, v54, v55
	v_cvt_pk_bf16_f32 v42, v48, v49
	v_cvt_pk_bf16_f32 v43, v50, v51
	v_cvt_pk_bf16_f32 v24, v36, v37
	v_cvt_pk_bf16_f32 v25, v38, v39
	v_cvt_pk_bf16_f32 v26, v32, v33
	v_cvt_pk_bf16_f32 v27, v34, v35
	global_store_dwordx4 v[28:29], v[12:15], off offset:256 nt
	v_cvt_pk_bf16_f32 v10, v16, v17
	v_cvt_pk_bf16_f32 v11, v18, v19
	v_lshl_add_u64 v[12:13], v[8:9], 0, v[150:151]
	v_cvt_pk_bf16_f32 v8, v20, v21
	v_cvt_pk_bf16_f32 v9, v22, v23
	v_cvt_pk_bf16_f32 v4, v4, v5
	v_cvt_pk_bf16_f32 v5, v6, v7
	v_cvt_pk_bf16_f32 v6, v0, v1
	v_cvt_pk_bf16_f32 v7, v2, v3
	s_and_b64 vcc, exec, s[2:3]
	s_mov_b32 s78, s16
	s_mov_b32 s8, s46
	s_mov_b64 s[54:55], s[50:51]
	s_mov_b64 s[52:53], s[48:49]
	global_store_dwordx4 v[154:155], v[124:127], off nt
	global_store_dwordx4 v[108:109], v[104:107], off nt
	global_store_dwordx4 v[92:93], v[88:91], off nt
	global_store_dwordx4 v[76:77], v[72:75], off nt
	global_store_dwordx4 v[76:77], v[68:71], off offset:256 nt
	global_store_dwordx4 v[64:65], v[60:63], off nt
	global_store_dwordx4 v[44:45], v[40:43], off nt
	global_store_dwordx4 v[28:29], v[24:27], off nt
	global_store_dwordx4 v[12:13], v[8:11], off nt
	global_store_dwordx4 v[12:13], v[4:7], off offset:256 nt
	s_cbranch_vccz .LBB0_110
	s_waitcnt vmcnt(0)
	s_cmpk_gt_u32 s33, 0xff
	s_cbranch_scc1 .LBB0_117
	s_barrier
